# stack23: attention builds the -m accumulator seed before the tile barrier instead of in the head of the compute segment (on top of stack22)
# baseline (speedup 1.0000x reference)
; DI int opaque_lane() { int l; asm volatile("v_mbcnt_lo_u32_b32 %0, -1, 0\n\tv_mbcnt_hi_u32_b32 %0, -1, %0" : "=v"(l)); return l; }
; DI void attn_unit(const bf16_t* Qb, const bf16_t* Kb, const bf16_t* Vt, bf16_t* MIX, int b, int h, int qb, char* lds, int tid_in) {
;     const int lane = opaque_lane(), wave = tid_in >> 6, tid = wave * 64 + lane, r = lane & 31, hh = lane >> 5;
;     const size_t rowbase = (size_t)b * SEQ; const int q0 = qb * 256;
;     bf16x8 qr[6];
;     { const bf16_t* qp = Qb + (rowbase + q0 + 32 * wave + r) * QW + h * 96 + 8 * hh;
; #pragma unroll
;         for (int ds = 0; ds < 6; ++ds) qr[ds] = *(const bf16x8*)(qp + 16 * ds); }
;     f32x16 o0 = {}, o1 = {};
;     float m_run = 0.f, l_run = 0.f;
;     const int NT = 2 * (qb + 1);
;     const bf16_t* Kh = Kb + rowbase * QW + h * 96; const bf16_t* Vh = Vt + (size_t)(b * 8 + h) * 64 * SEQ;
;     float* wsf = (float*)(lds + A_SC) + wave * 32;
;     const int qabs = q0 + 32 * wave + r;
;     u32x4 kreg[3], vreg[2];
;     int kgo[3], klo[3], vgo[2], vlo[2];
; #pragma unroll
;     for (int i = 0; i < 3; ++i) { const int q = tid + 512 * i, kv = q / 12, ck = q % 12; kgo[i] = kv * QW + ck * 8; klo[i] = ck * 2048 + kv * 16; }
; #pragma unroll
;     for (int i = 0; i < 2; ++i) { const int q = tid + 512 * i, d = q >> 4, pc = q & 15; vgo[i] = d * SEQ + pc * 8; vlo[i] = AK_BYTES + d * AV_PITCH + (16 * (pc >> 1) + 4 * (pc & 1)) * 2; }
;     auto gload = [&](int t) {
;         const bf16_t* kt = Kh + (size_t)t * 128 * QW; const bf16_t* vt = Vh + t * 128;
; #pragma unroll
;         for (int i = 0; i < 3; ++i) kreg[i] = *(const u32x4*)(kt + kgo[i]);
; #pragma unroll
;         for (int i = 0; i < 2; ++i) vreg[i] = *(const u32x4*)(vt + vgo[i]);
;     };
;     auto lstore = [&](int buf) {
;         char* bb_ = lds + buf * ABUF;
; #pragma unroll
;         for (int i = 0; i < 3; ++i) *(u32x4*)(bb_ + klo[i]) = kreg[i];
; #pragma unroll
;         for (int i = 0; i < 2; ++i) { u32x2 lo; lo.x = vreg[i].x; lo.y = vreg[i].y; u32x2 hi; hi.x = vreg[i].z; hi.y = vreg[i].w;
;             *(u32x2*)(bb_ + vlo[i]) = lo; *(u32x2*)(bb_ + vlo[i] + 16) = hi; }
;     };
;     gload(0); lstore(0); __syncthreads();
; #pragma unroll
;     for (int ds = 0; ds < 6; ++ds) asm volatile("" : "+v"(qr[ds]));
.Lattn_prio_done:
	s_lshl_b32 s62, s2, 8
	v_mbcnt_lo_u32_b32 v16, -1, 0
	v_mbcnt_hi_u32_b32 v16, -1, v16
	v_lshl_add_u64 v[146:147], v[144:145], 0, s[62:63]
	v_and_b32_e32 v164, 31, v16
	v_or_b32_e32 v0, v146, v164
	v_mov_b64_e32 v[2:3], s[40:41]
	v_mad_u64_u32 v[2:3], s[22:23], v0, s14, v[2:3]
	v_add_u32_e32 v0, v16, v162
	v_mul_hi_i32 v4, v0, s6
	v_lshrrev_b32_e32 v5, 31, v4
	v_ashrrev_i32_e32 v4, 1, v4
	v_add_u32_e32 v17, v4, v5
	v_add_u32_e32 v5, 0x200, v0
	v_mul_hi_i32 v6, v5, s6
	v_lshrrev_b32_e32 v7, 31, v6
	v_ashrrev_i32_e32 v6, 1, v6
	v_add_u32_e32 v19, v6, v7
	v_add_u32_e32 v7, 0x400, v0
	v_mul_hi_i32 v8, v7, s6
	v_lshrrev_b32_e32 v9, 31, v8
	v_ashrrev_i32_e32 v8, 1, v8
	v_mul_lo_u32 v4, v17, 12
	v_add_u32_e32 v21, v8, v9
	v_sub_u32_e32 v18, v0, v4
	v_mul_lo_u32 v4, v17, s18
	v_mul_lo_u32 v6, v19, 12
	v_mul_lo_u32 v8, v21, 12
	v_lshl_add_u32 v4, v18, 3, v4
	v_sub_u32_e32 v20, v5, v6
	v_mul_lo_u32 v6, v19, s18
	v_sub_u32_e32 v22, v7, v8
	v_mul_lo_u32 v7, v21, s18
	v_lshlrev_b32_e32 v23, 3, v16
	v_lshl_add_u32 v6, v20, 3, v6
	v_lshl_add_u32 v8, v22, 3, v7
	v_and_b32_e32 v24, 0x78, v23
	v_ashrrev_i32_e32 v25, 4, v0
	v_ashrrev_i32_e32 v26, 4, v5
	v_ashrrev_i32_e32 v5, 31, v4
	v_lshl_or_b32 v10, v25, 12, v24
	v_lshlrev_b64 v[4:5], 1, v[4:5]
	v_ashrrev_i32_e32 v7, 31, v6
	v_ashrrev_i32_e32 v9, 31, v8
	v_lshl_add_u64 v[12:13], s[44:45], 0, v[4:5]
	v_lshlrev_b64 v[6:7], 1, v[6:7]
	v_lshlrev_b64 v[8:9], 1, v[8:9]
	v_ashrrev_i32_e32 v11, 31, v10
	v_lshl_add_u64 v[14:15], s[44:45], 0, v[6:7]
	global_load_dwordx4 v[98:101], v[12:13], off
	global_load_dwordx4 v[102:105], v[14:15], off
	v_lshl_add_u64 v[12:13], s[44:45], 0, v[8:9]
	v_lshlrev_b64 v[10:11], 1, v[10:11]
	global_load_dwordx4 v[106:109], v[12:13], off
	v_lshl_add_u64 v[12:13], s[42:43], 0, v[10:11]
	global_load_dwordx4 v[110:113], v[12:13], off
	v_lshl_or_b32 v12, v26, 12, v24
	v_ashrrev_i32_e32 v13, 31, v12
	v_lshlrev_b64 v[12:13], 1, v[12:13]
	v_ashrrev_i32_e32 v165, 5, v16
	v_lshl_add_u64 v[14:15], s[42:43], 0, v[12:13]
	global_load_dwordx4 v[114:117], v[14:15], off
	v_lshlrev_b32_e32 v14, 3, v165
	v_mad_i32_i24 v3, v147, s14, v3
	v_ashrrev_i32_e32 v15, 31, v14
	v_lshl_add_u64 v[2:3], v[14:15], 1, v[2:3]
	global_load_dwordx4 v[118:121], v[2:3], off
	global_load_dwordx4 v[122:125], v[2:3], off offset:32
	global_load_dwordx4 v[126:129], v[2:3], off offset:64
	global_load_dwordx4 v[130:133], v[2:3], off offset:96
	global_load_dwordx4 v[134:137], v[2:3], off offset:128
	global_load_dwordx4 v[138:141], v[2:3], off offset:160
	v_lshlrev_b32_e32 v0, 4, v16
	v_and_b32_e32 v0, 0xe0, v0
	v_lshlrev_b32_e32 v2, 4, v17
	v_and_or_b32 v0, v23, 8, v0
	v_lshlrev_b32_e32 v3, 4, v19
	v_lshlrev_b32_e32 v14, 4, v21
	v_lshl_add_u32 v167, v18, 11, v2
	v_mad_u64_u32 v[148:149], s[22:23], v25, s21, v[0:1]
	v_lshl_add_u32 v168, v20, 11, v3
	v_lshl_add_u32 v169, v22, 11, v14
	v_and_b32_e32 v249, 7, v18
	v_lshlrev_b32_e32 v249, 4, v249
	v_xor_b32_e32 v167, v167, v249
	v_and_b32_e32 v249, 7, v20
	v_lshlrev_b32_e32 v249, 4, v249
	v_xor_b32_e32 v168, v168, v249
	v_and_b32_e32 v249, 7, v22
	v_lshlrev_b32_e32 v249, 4, v249
	v_xor_b32_e32 v169, v169, v249
	v_add_u32_e32 v2, 0, v167
	v_mad_u64_u32 v[150:151], s[22:23], v26, s21, v[0:1]
	v_add_u32_e32 v3, 0, v168
	v_add_u32_e32 v14, 0, v169
	v_add_u32_e32 v0, 0, v150
	v_add_u32_e32 v0, 0x6000, v0
	v_mov_b32_e32 v15, v1
	v_lshl_add_u64 v[152:153], s[48:49], 0, v[4:5]
	v_lshl_add_u64 v[154:155], s[48:49], 0, v[6:7]
	v_lshl_add_u64 v[156:157], s[48:49], 0, v[8:9]
	v_lshl_add_u64 v[158:159], s[50:51], 0, v[10:11]
	v_lshl_add_u64 v[160:161], s[50:51], 0, v[12:13]
	v_mov_b32_e32 v4, v1
	v_mov_b32_e32 v5, v1
	v_mov_b32_e32 v6, v1
	v_mov_b32_e32 v7, v1
	v_mov_b32_e32 v8, v1
	v_mov_b32_e32 v9, v1
	v_mov_b32_e32 v10, v1
	s_waitcnt vmcnt(10)
	ds_write_b128 v2, v[98:101]
	s_waitcnt vmcnt(9)
	ds_write_b128 v3, v[102:105]
	s_waitcnt vmcnt(8)
	ds_write_b128 v14, v[106:109]
	v_add_u32_e32 v2, 0, v148
	v_add_u32_e32 v2, 0x6000, v2
	v_mov_b32_e32 v14, v1
	s_waitcnt vmcnt(7)
	ds_write2_b64 v2, v[110:111], v[112:113] offset1:2
	v_mov_b32_e32 v2, v1
	v_mov_b32_e32 v3, v1
	v_mov_b32_e32 v11, v1
	v_mov_b32_e32 v12, v1
	v_mov_b32_e32 v13, v1
	s_waitcnt vmcnt(6)
	ds_write2_b64 v0, v[114:115], v[116:117] offset1:2
	v_mov_b32_e32 v0, v1
	v_mov_b64_e32 v[32:33], v[14:15]
	s_lshl_b32 s61, s2, 1
	v_add_u32_e32 v166, s62, v142
	v_cmp_gt_u32_e64 s[38:39], 32, v16
	v_lshlrev_b32_e32 v176, 4, v165
	v_mov_b64_e32 v[30:31], v[12:13]
	v_mov_b64_e32 v[28:29], v[10:11]
	v_mov_b64_e32 v[26:27], v[8:9]
	v_mov_b64_e32 v[24:25], v[6:7]
	v_mov_b64_e32 v[22:23], v[4:5]
	v_mov_b64_e32 v[20:21], v[2:3]
	v_mov_b64_e32 v[18:19], v[0:1]
	v_mov_b64_e32 v[16:17], v[14:15]
	s_mov_b32 s60, 1
	s_add_i32 s61, s61, 2
	v_or_b32_e32 v170, v164, v166
	v_or_b32_e32 v171, 31, v166
	v_lshlrev_b32_e32 v172, 11, v165
	v_lshlrev_b32_e32 v173, 4, v164
	v_lshlrev_b32_e32 v249, 4, v165
	v_xor_b32_e32 v173, v173, v249
	v_lshlrev_b32_e32 v174, 2, v165
	v_lshl_add_u32 v151, v164, 2, v163
	v_mul_u32_u24_e32 v175, 0x110, v164
	v_add_u32_e32 v149, v163, v176
	s_addk_i32 s62, 0x100
	s_mov_b32 s74, 0
	v_mov_b32_e32 v177, 0
	v_mov_b64_e32 v[14:15], v[12:13]
	v_mov_b64_e32 v[12:13], v[10:11]
	v_mov_b64_e32 v[10:11], v[8:9]
	v_mov_b64_e32 v[8:9], v[6:7]
	v_mov_b64_e32 v[6:7], v[4:5]
	v_mov_b64_e32 v[4:5], v[2:3]
	v_mov_b64_e32 v[2:3], v[0:1]
	v_mov_b32_e32 v0, 0
	v_xor_b32_e32 v34, 0x80000000, v177
	v_mov_b32_e32 v35, v34
	v_mov_b32_e32 v36, v34
	v_mov_b32_e32 v37, v34
	v_mov_b32_e32 v38, v34
	v_mov_b32_e32 v39, v34
	v_mov_b32_e32 v40, v34
	v_mov_b32_e32 v41, v34
	v_mov_b32_e32 v42, v34
	v_mov_b32_e32 v43, v34
	v_mov_b32_e32 v44, v34
	v_mov_b32_e32 v45, v34
	v_mov_b32_e32 v46, v34
	v_mov_b32_e32 v47, v34
	v_mov_b32_e32 v48, v34
	v_mov_b32_e32 v49, v34
	s_waitcnt lgkmcnt(0)
	s_barrier
	s_waitcnt vmcnt(5)
	s_waitcnt vmcnt(4)
	s_waitcnt vmcnt(3)
	s_waitcnt vmcnt(2)
	s_waitcnt vmcnt(1)
	s_waitcnt vmcnt(0)
	s_branch .LBB0_452
; #define MFMA32(a, b, c) __builtin_amdgcn_mfma_f32_32x32x16_bf16((a), (b), (c), 0, 0, 0)
; DI void attn_unit(const bf16_t* Qb, const bf16_t* Kb, const bf16_t* Vt, bf16_t* MIX, int b, int h, int qb, char* lds, int tid_in) {
;     ...
;     for (int t = 0; t < NT; ++t) {
;         const int buf = t & 1;
;         if (t + 1 < NT) gload(t + 1);
;         const int kv0 = t * 128;
;         if (kv0 <= q0 + 32 * wave + 31) {
;             const char* kb_ = lds + buf * ABUF; const char* vb_ = kb_ + AK_BYTES;
;             f32x16 p[4];
;             f32x16 negm;
; #pragma unroll
;             for (int i = 0; i < 16; ++i) negm[i] = -m_run;
; #pragma unroll
;             for (int kb = 0; kb < 4; ++kb) p[kb] = negm;
;             {
;                 bf16x8 kf[2][4];
; #pragma unroll
;                 for (int kb = 0; kb < 4; ++kb) kf[0][kb] = *(const bf16x8*)(kb_ + hh * 2048 + (32 * kb + r) * 16);
; #pragma unroll
;                 for (int ds = 0; ds < 6; ++ds) {
;                     if (ds + 1 < 6) {
; #pragma unroll
;                         for (int kb = 0; kb < 4; ++kb) kf[(ds + 1) & 1][kb] = *(const bf16x8*)(kb_ + (2 * (ds + 1) + hh) * 2048 + (32 * kb + r) * 16); }
;                     __builtin_amdgcn_sched_barrier(0);
;                     __builtin_amdgcn_s_setprio(1);
; #pragma unroll
;                     for (int kb = 0; kb < 4; ++kb) p[kb] = MFMA32(kf[ds & 1][kb], qr[ds], p[kb]);
;     ...
;         if (t + 1 < NT) lstore(buf ^ 1);
;         __syncthreads();
.LBB0_451:
	s_addk_i32 s74, 0x80
	s_add_i32 s60, s60, 1
	v_lshl_add_u64 v[152:153], v[152:153], 0, s[76:77]
	v_lshl_add_u64 v[154:155], v[154:155], 0, s[76:77]
	v_lshl_add_u64 v[156:157], v[156:157], 0, s[76:77]
	v_lshl_add_u64 v[158:159], v[158:159], 0, s[68:69]
	s_cmp_eq_u32 s62, s74
	v_lshl_add_u64 v[160:161], v[160:161], 0, s[68:69]
	v_xor_b32_e32 v34, 0x80000000, v177
	v_mov_b32_e32 v35, v34
	v_mov_b32_e32 v36, v34
	v_mov_b32_e32 v37, v34
	v_mov_b32_e32 v38, v34
	v_mov_b32_e32 v39, v34
	v_mov_b32_e32 v40, v34
	v_mov_b32_e32 v41, v34
	v_mov_b32_e32 v42, v34
	v_mov_b32_e32 v43, v34
	v_mov_b32_e32 v44, v34
	v_mov_b32_e32 v45, v34
	v_mov_b32_e32 v46, v34
	v_mov_b32_e32 v47, v34
	v_mov_b32_e32 v48, v34
	v_mov_b32_e32 v49, v34
	s_waitcnt lgkmcnt(0)
	s_barrier
	s_cbranch_scc1 .LBB0_470
.LBB0_452:
	s_cmp_lt_u32 s60, s61
	s_cselect_b64 s[52:53], -1, 0
	s_cmp_ge_u32 s60, s61
	s_cbranch_scc1 .LBB0_454
	v_lshl_add_u64 v[244:245], s[28:29], 0, v[152:153]
	v_lshl_add_u64 v[246:247], s[28:29], 0, v[154:155]
	global_load_dwordx4 v[98:101], v[244:245], off
	global_load_dwordx4 v[102:105], v[246:247], off
	v_lshl_add_u64 v[244:245], s[28:29], 0, v[156:157]
	v_lshl_add_u64 v[246:247], s[28:29], 0, v[158:159]
	global_load_dwordx4 v[106:109], v[244:245], off
	global_load_dwordx4 v[110:113], v[246:247], off
	v_lshl_add_u64 v[244:245], s[28:29], 0, v[160:161]
	global_load_dwordx4 v[114:117], v[244:245], off
.LBB0_454:
	s_add_i32 s2, s60, -1
	s_and_b32 s78, s2, 1
	v_cmp_le_i32_e32 vcc, s74, v171
	s_and_saveexec_b64 s[54:55], vcc
	s_cbranch_execz .LBB0_468
	s_mul_i32 s2, s78, 0xa400
	s_add_i32 s16, s2, 0
	v_add3_u32 v211, s16, v172, v173
	v_xor_b32_e32 v250, 32, v211
	v_xor_b32_e32 v251, 64, v211
	v_xor_b32_e32 v252, 0x60, v211
	ds_read_b128 v[50:53], v211
	ds_read_b128 v[54:57], v211 offset:512
	ds_read_b128 v[190:193], v211 offset:1024
	ds_read_b128 v[194:197], v211 offset:1536
	ds_read_b128 v[198:201], v250 offset:4096
	ds_read_b128 v[212:215], v250 offset:4608
	ds_read_b128 v[216:219], v250 offset:5120
	ds_read_b128 v[220:223], v250 offset:5632
	s_waitcnt lgkmcnt(7)
	v_mfma_f32_32x32x16_bf16 v[82:97], v[50:53], v[118:121], v[34:49]
	s_waitcnt lgkmcnt(6)
	v_mfma_f32_32x32x16_bf16 v[66:81], v[54:57], v[118:121], v[34:49]
	s_waitcnt lgkmcnt(5)
	v_mfma_f32_32x32x16_bf16 v[50:65], v[190:193], v[118:121], v[34:49]
	s_waitcnt lgkmcnt(4)
	v_mfma_f32_32x32x16_bf16 v[34:49], v[194:197], v[118:121], v[34:49]
	ds_read_b128 v[190:193], v251 offset:8192
	ds_read_b128 v[194:197], v251 offset:8704
	ds_read_b128 v[224:227], v251 offset:9216
	ds_read_b128 v[228:231], v251 offset:9728
	s_waitcnt lgkmcnt(7)
	v_mfma_f32_32x32x16_bf16 v[82:97], v[198:201], v[122:125], v[82:97]
	s_waitcnt lgkmcnt(6)
	v_mfma_f32_32x32x16_bf16 v[66:81], v[212:215], v[122:125], v[66:81]
	s_waitcnt lgkmcnt(5)
	v_mfma_f32_32x32x16_bf16 v[50:65], v[216:219], v[122:125], v[50:65]
	s_waitcnt lgkmcnt(4)
	v_mfma_f32_32x32x16_bf16 v[34:49], v[220:223], v[122:125], v[34:49]
	ds_read_b128 v[198:201], v252 offset:12288
	ds_read_b128 v[212:215], v252 offset:12800
	ds_read_b128 v[216:219], v252 offset:13312
	ds_read_b128 v[220:223], v252 offset:13824
	s_waitcnt lgkmcnt(7)
	v_mfma_f32_32x32x16_bf16 v[82:97], v[190:193], v[126:129], v[82:97]
	s_waitcnt lgkmcnt(6)
	v_mfma_f32_32x32x16_bf16 v[66:81], v[194:197], v[126:129], v[66:81]
	s_waitcnt lgkmcnt(5)
	v_mfma_f32_32x32x16_bf16 v[50:65], v[224:227], v[126:129], v[50:65]
	s_waitcnt lgkmcnt(4)
	v_mfma_f32_32x32x16_bf16 v[34:49], v[228:231], v[126:129], v[34:49]
	ds_read_b128 v[190:193], v211 offset:16384
	ds_read_b128 v[194:197], v211 offset:16896
	ds_read_b128 v[224:227], v211 offset:17408
	ds_read_b128 v[228:231], v211 offset:17920
	s_waitcnt lgkmcnt(7)
	v_mfma_f32_32x32x16_bf16 v[82:97], v[198:201], v[130:133], v[82:97]
	s_waitcnt lgkmcnt(6)
	v_mfma_f32_32x32x16_bf16 v[66:81], v[212:215], v[130:133], v[66:81]
	s_waitcnt lgkmcnt(5)
	v_mfma_f32_32x32x16_bf16 v[50:65], v[216:219], v[130:133], v[50:65]
	s_waitcnt lgkmcnt(4)
	v_mfma_f32_32x32x16_bf16 v[34:49], v[220:223], v[130:133], v[34:49]
	ds_read_b128 v[198:201], v250 offset:20480
	ds_read_b128 v[212:215], v250 offset:20992
	ds_read_b128 v[216:219], v250 offset:21504
	ds_read_b128 v[220:223], v250 offset:22016
	s_waitcnt lgkmcnt(7)
	v_mfma_f32_32x32x16_bf16 v[82:97], v[190:193], v[134:137], v[82:97]
	s_waitcnt lgkmcnt(6)
	v_mfma_f32_32x32x16_bf16 v[66:81], v[194:197], v[134:137], v[66:81]
	s_waitcnt lgkmcnt(5)
	v_mfma_f32_32x32x16_bf16 v[50:65], v[224:227], v[134:137], v[50:65]
	s_waitcnt lgkmcnt(4)
	v_mfma_f32_32x32x16_bf16 v[34:49], v[228:231], v[134:137], v[34:49]
	s_waitcnt lgkmcnt(3)
	v_mfma_f32_32x32x16_bf16 v[82:97], v[198:201], v[138:141], v[82:97]
	s_waitcnt lgkmcnt(2)
	v_mfma_f32_32x32x16_bf16 v[66:81], v[212:215], v[138:141], v[66:81]
	s_waitcnt lgkmcnt(1)
	v_mfma_f32_32x32x16_bf16 v[50:65], v[216:219], v[138:141], v[50:65]
	s_waitcnt lgkmcnt(0)
	v_mfma_f32_32x32x16_bf16 v[34:49], v[220:223], v[138:141], v[34:49]
	s_add_i32 s2, s74, 0x7f
	v_cmp_gt_i32_e32 vcc, s2, v166
	s_and_saveexec_b64 s[56:57], vcc
	s_cbranch_execz .LBB0_457
; DI int crow(int r, int h) { return (r & 3) + 8 * (r >> 2) + 4 * h; }
; DI void attn_unit(const bf16_t* Qb, const bf16_t* Kb, const bf16_t* Vt, bf16_t* MIX, int b, int h, int qb, char* lds, int tid_in) {
;     ...
;             if (kv0 + 127 > q0 + 32 * wave) {
; #pragma unroll
;                 for (int kb = 0; kb < 4; ++kb)
; #pragma unroll
;                     for (int i = 0; i < 16; ++i) { const int kv = kv0 + 32 * kb + crow(i, hh); if (kv > qabs) p[kb][i] = -1e30f; }
	v_add_u32_e32 v190, s74, v174
	v_cmp_lt_i32_e32 vcc, v190, v170
	v_add_u32_e32 v191, 2, v190
	s_nop 0
	v_cndmask_b32_e32 v83, v208, v83, vcc
	v_cmp_le_i32_e32 vcc, v190, v170
	s_nop 1
	v_cndmask_b32_e32 v82, v208, v82, vcc
	v_cmp_le_i32_e32 vcc, v191, v170
	v_add_u32_e32 v191, 3, v190
	s_nop 0
	v_cndmask_b32_e32 v84, v208, v84, vcc
	v_cmp_le_i32_e32 vcc, v191, v170
	v_add_u32_e32 v191, 8, v190
	s_nop 0
	v_cndmask_b32_e32 v85, v208, v85, vcc
	v_cmp_le_i32_e32 vcc, v191, v170
	v_add_u32_e32 v191, 9, v190
	s_nop 0
	v_cndmask_b32_e32 v86, v208, v86, vcc
	v_cmp_le_i32_e32 vcc, v191, v170
	v_add_u32_e32 v191, 10, v190
	s_nop 0
	v_cndmask_b32_e32 v87, v208, v87, vcc
	v_cmp_le_i32_e32 vcc, v191, v170
	v_add_u32_e32 v191, 11, v190
	s_nop 0
	v_cndmask_b32_e32 v88, v208, v88, vcc
	v_cmp_le_i32_e32 vcc, v191, v170
	v_add_u32_e32 v191, 16, v190
	s_nop 0
	v_cndmask_b32_e32 v89, v208, v89, vcc
	v_cmp_le_i32_e32 vcc, v191, v170
	v_add_u32_e32 v191, 17, v190
	s_nop 0
	v_cndmask_b32_e32 v90, v208, v90, vcc
	v_cmp_le_i32_e32 vcc, v191, v170
	v_add_u32_e32 v191, 18, v190
	s_nop 0
	v_cndmask_b32_e32 v91, v208, v91, vcc
	v_cmp_le_i32_e32 vcc, v191, v170
	v_add_u32_e32 v191, 19, v190
	s_nop 0
	v_cndmask_b32_e32 v92, v208, v92, vcc
	v_cmp_le_i32_e32 vcc, v191, v170
	v_add_u32_e32 v191, 24, v190
	s_nop 0
	v_cndmask_b32_e32 v93, v208, v93, vcc
	v_cmp_le_i32_e32 vcc, v191, v170
	v_add_u32_e32 v191, 25, v190
	s_nop 0
	v_cndmask_b32_e32 v94, v208, v94, vcc
	v_cmp_le_i32_e32 vcc, v191, v170
	v_add_u32_e32 v191, 26, v190
	s_nop 0
	v_cndmask_b32_e32 v95, v208, v95, vcc
	v_cmp_le_i32_e32 vcc, v191, v170
	v_add_u32_e32 v191, 27, v190
	s_nop 0
	v_cndmask_b32_e32 v96, v208, v96, vcc
	v_cmp_le_i32_e32 vcc, v191, v170
	v_add_u32_e32 v191, 32, v190
	s_nop 0
	v_cndmask_b32_e32 v97, v208, v97, vcc
	v_cmp_lt_i32_e32 vcc, v191, v170
	s_nop 1
	v_cndmask_b32_e32 v67, v208, v67, vcc
	v_cmp_le_i32_e32 vcc, v191, v170
	v_add_u32_e32 v191, 34, v190
	s_nop 0
	v_cndmask_b32_e32 v66, v208, v66, vcc
	v_cmp_le_i32_e32 vcc, v191, v170
	v_add_u32_e32 v191, 35, v190
	s_nop 0
	v_cndmask_b32_e32 v68, v208, v68, vcc
	v_cmp_le_i32_e32 vcc, v191, v170
	v_add_u32_e32 v191, 40, v190
	s_nop 0
	v_cndmask_b32_e32 v69, v208, v69, vcc
	v_cmp_le_i32_e32 vcc, v191, v170
	v_add_u32_e32 v191, 41, v190
	s_nop 0
	v_cndmask_b32_e32 v70, v208, v70, vcc
	v_cmp_le_i32_e32 vcc, v191, v170
	v_add_u32_e32 v191, 42, v190
	s_nop 0
	v_cndmask_b32_e32 v71, v208, v71, vcc
	v_cmp_le_i32_e32 vcc, v191, v170
	v_add_u32_e32 v191, 43, v190
	s_nop 0
	v_cndmask_b32_e32 v72, v208, v72, vcc
	v_cmp_le_i32_e32 vcc, v191, v170
	v_add_u32_e32 v191, 48, v190
	s_nop 0
	v_cndmask_b32_e32 v73, v208, v73, vcc
	v_cmp_le_i32_e32 vcc, v191, v170
	v_add_u32_e32 v191, 49, v190
	s_nop 0
	v_cndmask_b32_e32 v74, v208, v74, vcc
	v_cmp_le_i32_e32 vcc, v191, v170
	v_add_u32_e32 v191, 50, v190
	s_nop 0
	v_cndmask_b32_e32 v75, v208, v75, vcc
	v_cmp_le_i32_e32 vcc, v191, v170
	v_add_u32_e32 v191, 51, v190
	s_nop 0
	v_cndmask_b32_e32 v76, v208, v76, vcc
	v_cmp_le_i32_e32 vcc, v191, v170
	v_add_u32_e32 v191, 56, v190
	s_nop 0
	v_cndmask_b32_e32 v77, v208, v77, vcc
	v_cmp_le_i32_e32 vcc, v191, v170
	v_add_u32_e32 v191, 57, v190
	s_nop 0
	v_cndmask_b32_e32 v78, v208, v78, vcc
	v_cmp_le_i32_e32 vcc, v191, v170
	v_add_u32_e32 v191, 58, v190
	s_nop 0
	v_cndmask_b32_e32 v79, v208, v79, vcc
	v_cmp_le_i32_e32 vcc, v191, v170
	v_add_u32_e32 v191, 59, v190
	s_nop 0
	v_cndmask_b32_e32 v80, v208, v80, vcc
	v_cmp_le_i32_e32 vcc, v191, v170
	v_add_u32_e32 v191, 64, v190
	s_nop 0
	v_cndmask_b32_e32 v81, v208, v81, vcc
; DI int crow(int r, int h) { return (r & 3) + 8 * (r >> 2) + 4 * h; }
; DI void attn_unit(const bf16_t* Qb, const bf16_t* Kb, const bf16_t* Vt, bf16_t* MIX, int b, int h, int qb, char* lds, int tid_in) {
;     ...
;             if (kv0 + 127 > q0 + 32 * wave) {
; #pragma unroll
;                 for (int kb = 0; kb < 4; ++kb)
; #pragma unroll
;                     for (int i = 0; i < 16; ++i) { const int kv = kv0 + 32 * kb + crow(i, hh); if (kv > qabs) p[kb][i] = -1e30f; }
	v_cmp_lt_i32_e32 vcc, v191, v170
	s_nop 1
	v_cndmask_b32_e32 v51, v208, v51, vcc
	v_cmp_le_i32_e32 vcc, v191, v170
	v_add_u32_e32 v191, 0x42, v190
	s_nop 0
	v_cndmask_b32_e32 v50, v208, v50, vcc
	v_cmp_le_i32_e32 vcc, v191, v170
	v_add_u32_e32 v191, 0x43, v190
	s_nop 0
	v_cndmask_b32_e32 v52, v208, v52, vcc
	v_cmp_le_i32_e32 vcc, v191, v170
	v_add_u32_e32 v191, 0x48, v190
	s_nop 0
	v_cndmask_b32_e32 v53, v208, v53, vcc
	v_cmp_le_i32_e32 vcc, v191, v170
	v_add_u32_e32 v191, 0x49, v190
	s_nop 0
	v_cndmask_b32_e32 v54, v208, v54, vcc
	v_cmp_le_i32_e32 vcc, v191, v170
	v_add_u32_e32 v191, 0x4a, v190
	s_nop 0
	v_cndmask_b32_e32 v55, v208, v55, vcc
	v_cmp_le_i32_e32 vcc, v191, v170
	v_add_u32_e32 v191, 0x4b, v190
	s_nop 0
	v_cndmask_b32_e32 v56, v208, v56, vcc
	v_cmp_le_i32_e32 vcc, v191, v170
	v_add_u32_e32 v191, 0x50, v190
	s_nop 0
	v_cndmask_b32_e32 v57, v208, v57, vcc
	v_cmp_le_i32_e32 vcc, v191, v170
	v_add_u32_e32 v191, 0x51, v190
	s_nop 0
	v_cndmask_b32_e32 v58, v208, v58, vcc
	v_cmp_le_i32_e32 vcc, v191, v170
	v_add_u32_e32 v191, 0x52, v190
	s_nop 0
	v_cndmask_b32_e32 v59, v208, v59, vcc
	v_cmp_le_i32_e32 vcc, v191, v170
	v_add_u32_e32 v191, 0x53, v190
	s_nop 0
	v_cndmask_b32_e32 v60, v208, v60, vcc
	v_cmp_le_i32_e32 vcc, v191, v170
	v_add_u32_e32 v191, 0x58, v190
	s_nop 0
	v_cndmask_b32_e32 v61, v208, v61, vcc
	v_cmp_le_i32_e32 vcc, v191, v170
	v_add_u32_e32 v191, 0x59, v190
	s_nop 0
	v_cndmask_b32_e32 v62, v208, v62, vcc
	v_cmp_le_i32_e32 vcc, v191, v170
	v_add_u32_e32 v191, 0x5a, v190
	s_nop 0
	v_cndmask_b32_e32 v63, v208, v63, vcc
	v_cmp_le_i32_e32 vcc, v191, v170
	v_add_u32_e32 v191, 0x5b, v190
	s_nop 0
	v_cndmask_b32_e32 v64, v208, v64, vcc
	v_cmp_le_i32_e32 vcc, v191, v170
	v_add_u32_e32 v191, 0x60, v190
	s_nop 0
	v_cndmask_b32_e32 v65, v208, v65, vcc
	v_cmp_lt_i32_e32 vcc, v191, v170
	s_nop 1
	v_cndmask_b32_e32 v35, v208, v35, vcc
	v_cmp_le_i32_e32 vcc, v191, v170
	v_add_u32_e32 v191, 0x62, v190
	s_nop 0
	v_cndmask_b32_e32 v34, v208, v34, vcc
	v_cmp_le_i32_e32 vcc, v191, v170
	v_add_u32_e32 v191, 0x63, v190
	s_nop 0
	v_cndmask_b32_e32 v36, v208, v36, vcc
	v_cmp_le_i32_e32 vcc, v191, v170
	v_add_u32_e32 v191, 0x68, v190
	s_nop 0
	v_cndmask_b32_e32 v37, v208, v37, vcc
	v_cmp_le_i32_e32 vcc, v191, v170
	v_add_u32_e32 v191, 0x69, v190
	s_nop 0
	v_cndmask_b32_e32 v38, v208, v38, vcc
	v_cmp_le_i32_e32 vcc, v191, v170
	v_add_u32_e32 v191, 0x6a, v190
	s_nop 0
	v_cndmask_b32_e32 v39, v208, v39, vcc
	v_cmp_le_i32_e32 vcc, v191, v170
	v_add_u32_e32 v191, 0x6b, v190
	s_nop 0
	v_cndmask_b32_e32 v40, v208, v40, vcc
	v_cmp_le_i32_e32 vcc, v191, v170
	v_add_u32_e32 v191, 0x70, v190
	s_nop 0
	v_cndmask_b32_e32 v41, v208, v41, vcc
	v_cmp_le_i32_e32 vcc, v191, v170
	v_add_u32_e32 v191, 0x71, v190
	s_nop 0
	v_cndmask_b32_e32 v42, v208, v42, vcc
	v_cmp_le_i32_e32 vcc, v191, v170
	v_add_u32_e32 v191, 0x72, v190
	s_nop 0
	v_cndmask_b32_e32 v43, v208, v43, vcc
	v_cmp_le_i32_e32 vcc, v191, v170
	v_add_u32_e32 v191, 0x73, v190
	s_nop 0
	v_cndmask_b32_e32 v44, v208, v44, vcc
	v_cmp_le_i32_e32 vcc, v191, v170
	v_add_u32_e32 v191, 0x78, v190
	s_nop 0
	v_cndmask_b32_e32 v45, v208, v45, vcc
	v_cmp_le_i32_e32 vcc, v191, v170
	v_add_u32_e32 v191, 0x79, v190
	s_nop 0
	v_cndmask_b32_e32 v46, v208, v46, vcc
	v_cmp_le_i32_e32 vcc, v191, v170
	v_add_u32_e32 v191, 0x7a, v190
	v_add_u32_e32 v190, 0x7b, v190
	v_cndmask_b32_e32 v47, v208, v47, vcc
	v_cmp_le_i32_e32 vcc, v191, v170
	s_nop 1
	v_cndmask_b32_e32 v48, v208, v48, vcc
	v_cmp_le_i32_e32 vcc, v190, v170
	s_nop 1
	v_cndmask_b32_e32 v49, v208, v49, vcc
